# GLA combine: first-segment state loads overlap the first combine iteration's loads (one fewer serial memory round trip)
# speedup vs baseline: 1.0088x; 1.0088x over previous
; __device__ __forceinline__ void gla_scan(const Params& P, LAS unsigned char* lds, int bh, int seg, int nseg, bool dry) {
;     ...
;         for (int i = 0; i < seg; ++i) {
;             const char* src = (const char*)(SL + (size_t)(bh * 3 + i) * 32768); const char* dsrc = (const char*)(DL + (size_t)(bh * 4 + i) * 128);
; #pragma unroll
;             for (int kt = 0; kt < 8; ++kt) {
;                 const f32x4 dv = i ? *(const f32x4*)(dsrc + (size_t)((unsigned)g * 16u + (unsigned)(64 * kt))) : (f32x4){0.f, 0.f, 0.f, 0.f};
; #pragma unroll
;                 for (int vt = 0; vt < 2; ++vt) S[kt][vt] = S[kt][vt] * dv + *(const f32x4*)(src + (size_t)((unsigned)tid * 16u + (unsigned)((kt * 2 + vt) * 8192)));
;                 asm volatile("" : "+v"(S[kt][0]), "+v"(S[kt][1]) :: "memory");
;             }
.LBB0_689:
	s_or_b64 exec, exec, s[4:5]
	s_mul_i32 s9, s1, 0x60000
	v_lshlrev_b32_e32 v66, 4, v114
	s_add_u32 s4, s18, s9
	s_addc_u32 s5, s19, 0
	v_add_u32_e32 v68, 0x2000, v66
	s_barrier
	v_add_u32_e32 v70, 0x4000, v66
	v_add_u32_e32 v72, 0x6000, v66
	v_add_u32_e32 v74, 0x8000, v66
	v_add_u32_e32 v76, 0xa000, v66
	v_add_u32_e32 v78, 0xc000, v66
	v_add_u32_e32 v80, 0xe000, v66
	v_add_u32_e32 v82, 0x10000, v66
	v_add_u32_e32 v84, 0x12000, v66
	v_add_u32_e32 v86, 0x14000, v66
	v_add_u32_e32 v88, 0x16000, v66
	v_add_u32_e32 v90, 0x18000, v66
	v_add_u32_e32 v92, 0x1a000, v66
	v_add_u32_e32 v94, 0x1c000, v66
	v_add_u32_e32 v96, 0x1e000, v66
	global_load_dwordx4 v[32:35], v66, s[4:5]
	global_load_dwordx4 v[0:3], v68, s[4:5]
	global_load_dwordx4 v[4:7], v70, s[4:5]
	global_load_dwordx4 v[8:11], v72, s[4:5]
	global_load_dwordx4 v[12:15], v74, s[4:5]
	global_load_dwordx4 v[16:19], v76, s[4:5]
	global_load_dwordx4 v[20:23], v78, s[4:5]
	global_load_dwordx4 v[24:27], v80, s[4:5]
	global_load_dwordx4 v[36:39], v82, s[4:5]
	global_load_dwordx4 v[28:31], v84, s[4:5]
	global_load_dwordx4 v[40:43], v86, s[4:5]
	global_load_dwordx4 v[44:47], v88, s[4:5]
	global_load_dwordx4 v[48:51], v90, s[4:5]
	global_load_dwordx4 v[52:55], v92, s[4:5]
	global_load_dwordx4 v[56:59], v94, s[4:5]
	global_load_dwordx4 v[60:63], v96, s[4:5]
	s_cmp_eq_u32 s3, 1
	s_mov_b32 s5, 0
	s_cbranch_scc0 .Lcmb_multi
	s_waitcnt vmcnt(0)
	v_pk_add_f32 v[34:35], v[34:35], 0 op_sel_hi:[1,0]
	v_pk_add_f32 v[32:33], v[32:33], 0 op_sel_hi:[1,0]
	v_pk_add_f32 v[2:3], v[2:3], 0 op_sel_hi:[1,0]
	v_pk_add_f32 v[0:1], v[0:1], 0 op_sel_hi:[1,0]
	v_pk_add_f32 v[6:7], v[6:7], 0 op_sel_hi:[1,0]
	v_pk_add_f32 v[4:5], v[4:5], 0 op_sel_hi:[1,0]
	v_pk_add_f32 v[10:11], v[10:11], 0 op_sel_hi:[1,0]
	v_pk_add_f32 v[8:9], v[8:9], 0 op_sel_hi:[1,0]
	v_pk_add_f32 v[14:15], v[14:15], 0 op_sel_hi:[1,0]
	v_pk_add_f32 v[12:13], v[12:13], 0 op_sel_hi:[1,0]
	v_pk_add_f32 v[18:19], v[18:19], 0 op_sel_hi:[1,0]
	v_pk_add_f32 v[16:17], v[16:17], 0 op_sel_hi:[1,0]
	v_pk_add_f32 v[22:23], v[22:23], 0 op_sel_hi:[1,0]
	v_pk_add_f32 v[20:21], v[20:21], 0 op_sel_hi:[1,0]
	v_pk_add_f32 v[26:27], v[26:27], 0 op_sel_hi:[1,0]
	v_pk_add_f32 v[24:25], v[24:25], 0 op_sel_hi:[1,0]
	v_pk_add_f32 v[38:39], v[38:39], 0 op_sel_hi:[1,0]
	v_pk_add_f32 v[36:37], v[36:37], 0 op_sel_hi:[1,0]
	v_pk_add_f32 v[30:31], v[30:31], 0 op_sel_hi:[1,0]
	v_pk_add_f32 v[28:29], v[28:29], 0 op_sel_hi:[1,0]
	v_pk_add_f32 v[42:43], v[42:43], 0 op_sel_hi:[1,0]
	v_pk_add_f32 v[40:41], v[40:41], 0 op_sel_hi:[1,0]
	v_pk_add_f32 v[46:47], v[46:47], 0 op_sel_hi:[1,0]
	v_pk_add_f32 v[44:45], v[44:45], 0 op_sel_hi:[1,0]
	v_pk_add_f32 v[50:51], v[50:51], 0 op_sel_hi:[1,0]
	v_pk_add_f32 v[48:49], v[48:49], 0 op_sel_hi:[1,0]
	v_pk_add_f32 v[54:55], v[54:55], 0 op_sel_hi:[1,0]
	v_pk_add_f32 v[52:53], v[52:53], 0 op_sel_hi:[1,0]
	v_pk_add_f32 v[58:59], v[58:59], 0 op_sel_hi:[1,0]
	v_pk_add_f32 v[56:57], v[56:57], 0 op_sel_hi:[1,0]
	v_pk_add_f32 v[62:63], v[62:63], 0 op_sel_hi:[1,0]
	v_pk_add_f32 v[60:61], v[60:61], 0 op_sel_hi:[1,0]
	s_branch .LBB0_692
.Lcmb_multi:
	v_mov_b32_e32 v67, 0
	s_lshl_b32 s4, s1, 2
	v_lshlrev_b32_e32 v64, 4, v100
	v_mov_b32_e32 v65, v67
	s_add_i32 s8, s3, -1
	s_or_b32 s4, s4, 1
	v_mov_b32_e32 v69, v67
	v_mov_b32_e32 v71, v67
	v_mov_b32_e32 v73, v67
	v_mov_b32_e32 v75, v67
	v_mov_b32_e32 v77, v67
	v_mov_b32_e32 v79, v67
	v_mov_b32_e32 v81, v67
	v_mov_b32_e32 v83, v67
	v_mov_b32_e32 v85, v67
	v_mov_b32_e32 v87, v67
	v_mov_b32_e32 v89, v67
	v_mov_b32_e32 v91, v67
	v_mov_b32_e32 v93, v67
	v_mov_b32_e32 v95, v67
	v_mov_b32_e32 v97, v67
	v_lshl_add_u64 v[64:65], s[6:7], 0, v[64:65]
	s_mov_b64 s[10:11], 0x1f020000
	s_add_u32 s6, s70, s9
	v_lshl_add_u64 v[66:67], v[66:67], 0, s[10:11]
	s_addc_u32 s7, s71, 0
	v_lshl_add_u64 v[68:69], v[68:69], 0, s[10:11]
	v_lshl_add_u64 v[70:71], v[70:71], 0, s[10:11]
	v_lshl_add_u64 v[72:73], v[72:73], 0, s[10:11]
	v_lshl_add_u64 v[74:75], v[74:75], 0, s[10:11]
	v_lshl_add_u64 v[76:77], v[76:77], 0, s[10:11]
	v_lshl_add_u64 v[78:79], v[78:79], 0, s[10:11]
	v_lshl_add_u64 v[80:81], v[80:81], 0, s[10:11]
	v_lshl_add_u64 v[82:83], v[82:83], 0, s[10:11]
	v_lshl_add_u64 v[84:85], v[84:85], 0, s[10:11]
	v_lshl_add_u64 v[86:87], v[86:87], 0, s[10:11]
	v_lshl_add_u64 v[88:89], v[88:89], 0, s[10:11]
	v_lshl_add_u64 v[90:91], v[90:91], 0, s[10:11]
	v_lshl_add_u64 v[92:93], v[92:93], 0, s[10:11]
	v_lshl_add_u64 v[94:95], v[94:95], 0, s[10:11]
	v_lshl_add_u64 v[96:97], v[96:97], 0, s[10:11]
; __device__ __forceinline__ void gla_scan(const Params& P, LAS unsigned char* lds, int bh, int seg, int nseg, bool dry) {
;     ...
;         for (int i = 0; i < seg; ++i) {
;             const char* src = (const char*)(SL + (size_t)(bh * 3 + i) * 32768); const char* dsrc = (const char*)(DL + (size_t)(bh * 4 + i) * 128);
; #pragma unroll
;             for (int kt = 0; kt < 8; ++kt) {
;                 const f32x4 dv = i ? *(const f32x4*)(dsrc + (size_t)((unsigned)g * 16u + (unsigned)(64 * kt))) : (f32x4){0.f, 0.f, 0.f, 0.f};
; #pragma unroll
;                 for (int vt = 0; vt < 2; ++vt) S[kt][vt] = S[kt][vt] * dv + *(const f32x4*)(src + (size_t)((unsigned)tid * 16u + (unsigned)((kt * 2 + vt) * 8192)));
;                 asm volatile("" : "+v"(S[kt][0]), "+v"(S[kt][1]) :: "memory");
;             }
.LBB0_691:
	s_lshl_b64 s[10:11], s[4:5], 9
	v_lshl_add_u64 v[98:99], v[64:65], 0, s[10:11]
	global_load_dwordx4 v[120:123], v[98:99], off
	global_load_dwordx4 v[124:127], v[98:99], off offset:64
	global_load_dwordx4 v[128:131], v[98:99], off offset:128
	global_load_dwordx4 v[132:135], v[98:99], off offset:192
	global_load_dwordx4 v[136:139], v[98:99], off offset:256
	global_load_dwordx4 v[140:143], v[98:99], off offset:320
	global_load_dwordx4 v[144:147], v[98:99], off offset:384
	global_load_dwordx4 v[148:151], v[98:99], off offset:448
	v_lshl_add_u64 v[116:117], s[6:7], 0, v[66:67]
	global_load_dwordx4 v[152:155], v[116:117], off
	v_lshl_add_u64 v[118:119], s[6:7], 0, v[68:69]
	global_load_dwordx4 v[156:159], v[118:119], off
	v_lshl_add_u64 v[116:117], s[6:7], 0, v[70:71]
	global_load_dwordx4 v[160:163], v[116:117], off
	v_lshl_add_u64 v[118:119], s[6:7], 0, v[72:73]
	global_load_dwordx4 v[164:167], v[118:119], off
	v_lshl_add_u64 v[116:117], s[6:7], 0, v[74:75]
	global_load_dwordx4 v[168:171], v[116:117], off
	v_lshl_add_u64 v[118:119], s[6:7], 0, v[76:77]
	global_load_dwordx4 v[172:175], v[118:119], off
	v_lshl_add_u64 v[116:117], s[6:7], 0, v[78:79]
	global_load_dwordx4 v[176:179], v[116:117], off
	v_lshl_add_u64 v[118:119], s[6:7], 0, v[80:81]
	global_load_dwordx4 v[180:183], v[118:119], off
	v_lshl_add_u64 v[116:117], s[6:7], 0, v[82:83]
	global_load_dwordx4 v[184:187], v[116:117], off
	v_lshl_add_u64 v[118:119], s[6:7], 0, v[84:85]
	global_load_dwordx4 v[188:191], v[118:119], off
	v_lshl_add_u64 v[116:117], s[6:7], 0, v[86:87]
	global_load_dwordx4 v[196:199], v[116:117], off
	v_lshl_add_u64 v[118:119], s[6:7], 0, v[88:89]
	global_load_dwordx4 v[200:203], v[118:119], off
	v_lshl_add_u64 v[116:117], s[6:7], 0, v[90:91]
	global_load_dwordx4 v[204:207], v[116:117], off
	v_lshl_add_u64 v[118:119], s[6:7], 0, v[92:93]
	global_load_dwordx4 v[208:211], v[118:119], off
	v_lshl_add_u64 v[116:117], s[6:7], 0, v[94:95]
	global_load_dwordx4 v[212:215], v[116:117], off
	v_lshl_add_u64 v[118:119], s[6:7], 0, v[96:97]
	global_load_dwordx4 v[216:219], v[118:119], off
	s_add_i32 s8, s8, -1
	s_add_i32 s4, s4, 1
	s_add_u32 s6, s6, 0x20000
	s_addc_u32 s7, s7, 0
	s_cmp_lg_u32 s8, 0
	s_waitcnt vmcnt(0)
	v_pk_add_f32 v[34:35], v[34:35], 0 op_sel_hi:[1,0]
	v_pk_add_f32 v[32:33], v[32:33], 0 op_sel_hi:[1,0]
	v_pk_add_f32 v[2:3], v[2:3], 0 op_sel_hi:[1,0]
	v_pk_add_f32 v[0:1], v[0:1], 0 op_sel_hi:[1,0]
	v_pk_add_f32 v[6:7], v[6:7], 0 op_sel_hi:[1,0]
	v_pk_add_f32 v[4:5], v[4:5], 0 op_sel_hi:[1,0]
	v_pk_add_f32 v[10:11], v[10:11], 0 op_sel_hi:[1,0]
	v_pk_add_f32 v[8:9], v[8:9], 0 op_sel_hi:[1,0]
	v_pk_add_f32 v[14:15], v[14:15], 0 op_sel_hi:[1,0]
	v_pk_add_f32 v[12:13], v[12:13], 0 op_sel_hi:[1,0]
	v_pk_add_f32 v[18:19], v[18:19], 0 op_sel_hi:[1,0]
	v_pk_add_f32 v[16:17], v[16:17], 0 op_sel_hi:[1,0]
	v_pk_add_f32 v[22:23], v[22:23], 0 op_sel_hi:[1,0]
	v_pk_add_f32 v[20:21], v[20:21], 0 op_sel_hi:[1,0]
	v_pk_add_f32 v[26:27], v[26:27], 0 op_sel_hi:[1,0]
	v_pk_add_f32 v[24:25], v[24:25], 0 op_sel_hi:[1,0]
	v_pk_add_f32 v[38:39], v[38:39], 0 op_sel_hi:[1,0]
	v_pk_add_f32 v[36:37], v[36:37], 0 op_sel_hi:[1,0]
	v_pk_add_f32 v[30:31], v[30:31], 0 op_sel_hi:[1,0]
	v_pk_add_f32 v[28:29], v[28:29], 0 op_sel_hi:[1,0]
	v_pk_add_f32 v[42:43], v[42:43], 0 op_sel_hi:[1,0]
	v_pk_add_f32 v[40:41], v[40:41], 0 op_sel_hi:[1,0]
	v_pk_add_f32 v[46:47], v[46:47], 0 op_sel_hi:[1,0]
	v_pk_add_f32 v[44:45], v[44:45], 0 op_sel_hi:[1,0]
	v_pk_add_f32 v[50:51], v[50:51], 0 op_sel_hi:[1,0]
	v_pk_add_f32 v[48:49], v[48:49], 0 op_sel_hi:[1,0]
	v_pk_add_f32 v[54:55], v[54:55], 0 op_sel_hi:[1,0]
	v_pk_add_f32 v[52:53], v[52:53], 0 op_sel_hi:[1,0]
	v_pk_add_f32 v[58:59], v[58:59], 0 op_sel_hi:[1,0]
	v_pk_add_f32 v[56:57], v[56:57], 0 op_sel_hi:[1,0]
	v_pk_add_f32 v[62:63], v[62:63], 0 op_sel_hi:[1,0]
	v_pk_add_f32 v[60:61], v[60:61], 0 op_sel_hi:[1,0]
	v_pk_fma_f32 v[34:35], v[34:35], v[122:123], v[154:155]
	v_pk_fma_f32 v[32:33], v[32:33], v[120:121], v[152:153]
	v_pk_fma_f32 v[2:3], v[2:3], v[122:123], v[158:159]
	v_pk_fma_f32 v[0:1], v[0:1], v[120:121], v[156:157]
	v_pk_fma_f32 v[6:7], v[6:7], v[126:127], v[162:163]
	v_pk_fma_f32 v[4:5], v[4:5], v[124:125], v[160:161]
	v_pk_fma_f32 v[10:11], v[10:11], v[126:127], v[166:167]
	v_pk_fma_f32 v[8:9], v[8:9], v[124:125], v[164:165]
	v_pk_fma_f32 v[14:15], v[14:15], v[130:131], v[170:171]
	v_pk_fma_f32 v[12:13], v[12:13], v[128:129], v[168:169]
	v_pk_fma_f32 v[18:19], v[18:19], v[130:131], v[174:175]
	v_pk_fma_f32 v[16:17], v[16:17], v[128:129], v[172:173]
	v_pk_fma_f32 v[22:23], v[22:23], v[134:135], v[178:179]
	v_pk_fma_f32 v[20:21], v[20:21], v[132:133], v[176:177]
	v_pk_fma_f32 v[26:27], v[26:27], v[134:135], v[182:183]
	v_pk_fma_f32 v[24:25], v[24:25], v[132:133], v[180:181]
	v_pk_fma_f32 v[38:39], v[38:39], v[138:139], v[186:187]
	v_pk_fma_f32 v[36:37], v[36:37], v[136:137], v[184:185]
	v_pk_fma_f32 v[30:31], v[30:31], v[138:139], v[190:191]
	v_pk_fma_f32 v[28:29], v[28:29], v[136:137], v[188:189]
	v_pk_fma_f32 v[42:43], v[42:43], v[142:143], v[198:199]
	v_pk_fma_f32 v[40:41], v[40:41], v[140:141], v[196:197]
	v_pk_fma_f32 v[46:47], v[46:47], v[142:143], v[202:203]
	v_pk_fma_f32 v[44:45], v[44:45], v[140:141], v[200:201]
	v_pk_fma_f32 v[50:51], v[50:51], v[146:147], v[206:207]
	v_pk_fma_f32 v[48:49], v[48:49], v[144:145], v[204:205]
	v_pk_fma_f32 v[54:55], v[54:55], v[146:147], v[210:211]
	v_pk_fma_f32 v[52:53], v[52:53], v[144:145], v[208:209]
	v_pk_fma_f32 v[58:59], v[58:59], v[150:151], v[214:215]
	v_pk_fma_f32 v[56:57], v[56:57], v[148:149], v[212:213]
	v_pk_fma_f32 v[62:63], v[62:63], v[150:151], v[218:219]
	v_pk_fma_f32 v[60:61], v[60:61], v[148:149], v[216:217]
	s_cbranch_scc1 .LBB0_691
